# v38 + one wait state between the last P cvt_pk and its PV MFMA (hazard distance restored)
# speedup vs baseline: 1.0018x; 1.0018x over previous
.LBB0_812:
	s_or_b64 exec, exec, s[52:53]
	s_ashr_i32 s49, s48, 31
	s_lshl_b64 s[48:49], s[48:49], 2
	s_add_u32 s48, s3, s48
	s_addc_u32 s49, s82, s49
	s_waitcnt lgkmcnt(0)
	s_barrier
	global_load_dword v149, v195, s[48:49]
	ds_read_b128 v[178:181], v142
	ds_read_b128 v[182:185], v142 offset:32
	ds_read_b128 v[186:189], v142 offset:64
	s_waitcnt lgkmcnt(2)
	v_mfma_f32_32x32x16_bf16 v[66:81], v[178:181], v[34:37], 0
	v_lshl_add_u64 v[126:127], s[50:51], 1, v[118:119]
	s_and_b64 s[48:49], vcc, s[12:13]
	s_and_b64 s[50:51], vcc, s[14:15]
	s_and_b64 s[52:53], vcc, s[16:17]
	s_and_b64 s[54:55], vcc, s[18:19]
	s_and_b64 s[56:57], vcc, s[20:21]
	ds_read_b128 v[190:193], v142 offset:96
	s_waitcnt lgkmcnt(2)
	v_mfma_f32_32x32x16_bf16 v[66:81], v[182:185], v[106:109], v[66:81]
	s_and_b64 s[58:59], vcc, s[22:23]
	s_and_b64 s[60:61], vcc, s[24:25]
	s_and_b64 s[62:63], vcc, s[26:27]
	s_and_b64 s[64:65], vcc, s[28:29]
	s_and_b64 s[66:67], vcc, s[30:31]
	s_and_b64 s[68:69], vcc, s[34:35]
	s_and_b64 s[70:71], vcc, s[36:37]
	ds_read_b128 v[178:181], v143
	s_waitcnt lgkmcnt(2)
	v_mfma_f32_32x32x16_bf16 v[66:81], v[186:189], v[102:105], v[66:81]
	s_and_b64 s[72:73], vcc, s[38:39]
	s_and_b64 s[74:75], vcc, s[42:43]
	s_and_b64 s[76:77], vcc, s[44:45]
	s_and_b64 s[78:79], vcc, s[0:1]
	s_or_b32 s80, s80, s96
	s_cmp_eq_u32 s80, 0
	ds_read_b128 v[182:185], v143 offset:32
	s_waitcnt lgkmcnt(2)
	v_mfma_f32_32x32x16_bf16 v[66:81], v[190:193], v[98:101], v[66:81]
	s_cselect_b64 s[80:81], -1, 0
	s_mov_b32 s94, 0x3fb8aa3b
	v_or_b32_e32 v152, s97, v150
	s_add_i32 s2, s2, s86
	s_cmpk_lt_i32 s2, 0x200
	s_nop 4
	s_nop 0
	s_nop 0
	v_cndmask_b32_e64 v67, v245, v67, s[50:51]
	ds_read_b128 v[186:189], v143 offset:64
	s_waitcnt lgkmcnt(2)
	v_mfma_f32_32x32x16_bf16 v[50:65], v[178:181], v[34:37], 0
	v_cndmask_b32_e64 v68, v245, v68, s[52:53]
	v_cndmask_b32_e64 v69, v245, v69, s[54:55]
	v_cndmask_b32_e64 v70, v245, v70, s[56:57]
	v_cndmask_b32_e64 v71, v245, v71, s[58:59]
	v_cndmask_b32_e64 v72, v245, v72, s[60:61]
	v_cndmask_b32_e64 v75, v245, v75, s[66:67]
	ds_read_b128 v[190:193], v143 offset:96
	s_waitcnt lgkmcnt(2)
	v_mfma_f32_32x32x16_bf16 v[50:65], v[182:185], v[106:109], v[50:65]
	v_cndmask_b32_e64 v78, v245, v78, s[72:73]
	v_cndmask_b32_e64 v79, v245, v79, s[74:75]
	v_cndmask_b32_e64 v80, v245, v80, s[76:77]
	v_cndmask_b32_e64 v81, v245, v81, s[78:79]
	s_waitcnt vmcnt(0)
	v_mul_f32_e32 v151, 0x3fb8aa3b, v149
	ds_read_b128 v[178:181], v144
	s_waitcnt lgkmcnt(2)
	v_mfma_f32_32x32x16_bf16 v[50:65], v[186:189], v[102:105], v[50:65]
	ds_read_b128 v[182:185], v144 offset:32
	s_waitcnt lgkmcnt(2)
	v_mfma_f32_32x32x16_bf16 v[50:65], v[190:193], v[98:101], v[50:65]
	ds_read_b128 v[186:189], v144 offset:64
	s_waitcnt lgkmcnt(2)
	v_mfma_f32_32x32x16_bf16 v[18:33], v[178:181], v[34:37], 0
	s_nop 6
	s_nop 1
	v_cndmask_b32_e32 v50, v245, v50, vcc
	v_cndmask_b32_e32 v54, v245, v54, vcc
	v_cndmask_b32_e32 v59, v245, v59, vcc
	v_cndmask_b32_e32 v60, v245, v60, vcc
	v_cndmask_b32_e32 v153, v245, v61, vcc
	v_cndmask_b32_e32 v63, v245, v63, vcc
	ds_read_b128 v[190:193], v144 offset:96
	s_waitcnt lgkmcnt(2)
	v_mfma_f32_32x32x16_bf16 v[18:33], v[182:185], v[106:109], v[18:33]
	v_cndmask_b32_e32 v65, v245, v65, vcc
	ds_read_b128 v[178:181], v145
	s_waitcnt lgkmcnt(2)
	v_mfma_f32_32x32x16_bf16 v[18:33], v[186:189], v[102:105], v[18:33]
	ds_read_b128 v[182:185], v145 offset:32
	s_waitcnt lgkmcnt(2)
	v_mfma_f32_32x32x16_bf16 v[18:33], v[190:193], v[98:101], v[18:33]
	ds_read_b128 v[186:189], v145 offset:64
	s_waitcnt lgkmcnt(2)
	v_mfma_f32_32x32x16_bf16 v[2:17], v[178:181], v[34:37], 0
	s_nop 7
	s_nop 0
	v_cndmask_b32_e64 v158, v20, v245, s[80:81]
	v_cndmask_b32_e64 v159, v21, v245, s[80:81]
	v_cndmask_b32_e64 v160, v22, v245, s[80:81]
	v_cndmask_b32_e64 v161, v23, v245, s[80:81]
	v_cndmask_b32_e64 v162, v24, v245, s[80:81]
	v_cndmask_b32_e64 v163, v25, v245, s[80:81]
	v_cndmask_b32_e64 v164, v26, v245, s[80:81]
	ds_read_b128 v[190:193], v145 offset:96
	s_waitcnt lgkmcnt(2)
	v_mfma_f32_32x32x16_bf16 v[2:17], v[182:185], v[106:109], v[2:17]
	v_cndmask_b32_e64 v165, v27, v245, s[80:81]
	v_cndmask_b32_e64 v166, v28, v245, s[80:81]
	v_cndmask_b32_e64 v167, v29, v245, s[80:81]
	v_cndmask_b32_e64 v168, v30, v245, s[80:81]
	ds_read_b128 v[178:181], v146
	s_waitcnt lgkmcnt(2)
	v_mfma_f32_32x32x16_bf16 v[2:17], v[186:189], v[102:105], v[2:17]
	ds_read_b128 v[182:185], v146 offset:32
	s_waitcnt lgkmcnt(2)
	v_mfma_f32_32x32x16_bf16 v[2:17], v[190:193], v[98:101], v[2:17]
	ds_read_b128 v[186:189], v146 offset:64
	s_waitcnt lgkmcnt(2)
	v_mfma_f32_32x32x16_bf16 v[34:49], v[178:181], v[34:37], 0
	s_nop 7
	s_nop 0
	v_cndmask_b32_e64 v61, v5, v245, s[80:81]
	v_cndmask_b32_e64 v30, v14, v245, s[80:81]
	v_cndmask_b32_e64 v29, v15, v245, s[80:81]
	v_cndmask_b32_e64 v28, v16, v245, s[80:81]
	v_cndmask_b32_e64 v27, v17, v245, s[80:81]
	ds_read_b128 v[190:193], v146 offset:96
	s_waitcnt lgkmcnt(2)
	v_mfma_f32_32x32x16_bf16 v[34:49], v[182:185], v[106:109], v[34:49]
	v_cndmask_b32_e32 v154, v245, v62, vcc
	v_cndmask_b32_e32 v155, v245, v64, vcc
	v_cndmask_b32_e64 v156, v18, v245, s[80:81]
	v_cndmask_b32_e64 v157, v19, v245, s[80:81]
	v_cndmask_b32_e64 v64, v4, v245, s[80:81]
	s_waitcnt lgkmcnt(1)
	v_mfma_f32_32x32x16_bf16 v[34:49], v[186:189], v[102:105], v[34:49]
	v_cndmask_b32_e32 v106, v245, v55, vcc
	v_cndmask_b32_e32 v107, v245, v56, vcc
	v_cndmask_b32_e32 v108, v245, v57, vcc
	v_cndmask_b32_e32 v109, v245, v58, vcc
	v_cndmask_b32_e64 v58, v6, v245, s[80:81]
	v_cndmask_b32_e64 v57, v7, v245, s[80:81]
	s_waitcnt lgkmcnt(0)
	v_mfma_f32_32x32x16_bf16 v[34:49], v[190:193], v[98:101], v[34:49]
	v_cndmask_b32_e64 v98, v245, v66, s[48:49]
	v_max3_f32 v66, v151, v98, v67
	v_max3_f32 v66, v66, v68, v69
	v_max3_f32 v66, v66, v70, v71
	v_cndmask_b32_e64 v99, v245, v73, s[62:63]
	v_max3_f32 v66, v66, v72, v99
	v_cndmask_b32_e64 v100, v245, v74, s[64:65]
	v_max3_f32 v66, v66, v100, v75
	v_cndmask_b32_e64 v101, v245, v76, s[68:69]
	v_cndmask_b32_e64 v102, v245, v77, s[70:71]
	v_max3_f32 v66, v66, v101, v102
	v_max3_f32 v66, v66, v78, v79
	v_max3_f32 v66, v66, v80, v81
	v_cndmask_b32_e32 v103, v245, v51, vcc
	v_max3_f32 v51, v66, v50, v103
	v_cndmask_b32_e32 v104, v245, v52, vcc
	v_cndmask_b32_e32 v105, v245, v53, vcc
	v_max3_f32 v51, v51, v104, v105
	v_max3_f32 v51, v51, v54, v106
	v_max3_f32 v51, v51, v107, v108
	v_max3_f32 v51, v51, v109, v59
	v_max3_f32 v51, v51, v60, v153
	v_max3_f32 v51, v51, v154, v63
	v_max3_f32 v51, v51, v155, v65
	v_max3_f32 v18, v51, v156, v157
	v_max3_f32 v18, v18, v158, v159
	v_max3_f32 v18, v18, v160, v161
	v_max3_f32 v18, v18, v162, v163
	v_max3_f32 v18, v18, v164, v165
	v_max3_f32 v18, v18, v166, v167
	v_cndmask_b32_e64 v77, v31, v245, s[80:81]
	v_max3_f32 v18, v18, v168, v77
	v_cndmask_b32_e64 v76, v32, v245, s[80:81]
	v_cndmask_b32_e64 v74, v33, v245, s[80:81]
	v_max3_f32 v18, v18, v76, v74
	v_cndmask_b32_e64 v73, v2, v245, s[80:81]
	v_cndmask_b32_e64 v66, v3, v245, s[80:81]
	v_max3_f32 v2, v18, v73, v66
	v_max3_f32 v2, v2, v64, v61
	v_max3_f32 v2, v2, v58, v57
	v_cndmask_b32_e64 v55, v8, v245, s[80:81]
	v_cndmask_b32_e64 v53, v9, v245, s[80:81]
	v_max3_f32 v2, v2, v55, v53
	v_cndmask_b32_e64 v52, v10, v245, s[80:81]
	v_cndmask_b32_e64 v33, v11, v245, s[80:81]
	v_max3_f32 v2, v2, v52, v33
	v_cndmask_b32_e64 v32, v12, v245, s[80:81]
	v_cndmask_b32_e64 v31, v13, v245, s[80:81]
	v_max3_f32 v2, v2, v32, v31
	v_max3_f32 v2, v2, v30, v29
	v_max3_f32 v2, v2, v28, v27
	v_cndmask_b32_e64 v26, v34, v245, s[12:13]
	v_cndmask_b32_e64 v25, v245, v35, s[46:47]
	v_max3_f32 v2, v2, v26, v25
	v_cndmask_b32_e64 v24, v36, v245, s[16:17]
	v_cndmask_b32_e64 v23, v37, v245, s[18:19]
	v_max3_f32 v2, v2, v24, v23
	v_cndmask_b32_e64 v22, v38, v245, s[20:21]
	v_cndmask_b32_e64 v21, v39, v245, s[22:23]
	v_max3_f32 v2, v2, v22, v21
	v_cndmask_b32_e64 v20, v40, v245, s[24:25]
	v_cndmask_b32_e64 v19, v41, v245, s[26:27]
	v_max3_f32 v2, v2, v20, v19
	v_cndmask_b32_e64 v18, v42, v245, s[28:29]
	v_cndmask_b32_e64 v17, v43, v245, s[30:31]
	v_max3_f32 v2, v2, v18, v17
	v_cndmask_b32_e64 v16, v44, v245, s[34:35]
	v_cndmask_b32_e64 v15, v45, v245, s[36:37]
	v_max3_f32 v2, v2, v16, v15
	v_cndmask_b32_e64 v14, v46, v245, s[38:39]
	v_cndmask_b32_e64 v13, v47, v245, s[42:43]
	v_max3_f32 v2, v2, v14, v13
	v_cndmask_b32_e64 v12, v48, v245, s[44:45]
	v_cndmask_b32_e64 v11, v49, v245, s[0:1]
	v_max3_f32 v2, v2, v12, v11
	v_mov_b32_e32 v3, v2
	v_mov_b32_e32 v206, v2
	s_nop 1
	v_permlane32_swap_b32 v3, v206
	v_max_f32_e32 v10, v3, v206
	v_sub_f32_e32 v2, v98, v10
	v_exp_f32_e32 v2, v2
	v_sub_f32_e32 v3, v67, v10
	v_exp_f32_e32 v3, v3
	v_sub_f32_e32 v35, v100, v10
	v_add_f32_e32 v4, 0, v2
	v_exp_f32_e32 v35, v35
	v_add_f32_e32 v5, v3, v4
	v_sub_f32_e32 v4, v68, v10
	v_exp_f32_e32 v4, v4
	v_sub_f32_e32 v36, v75, v10
	v_exp_f32_e32 v36, v36
	v_sub_f32_e32 v37, v101, v10
	v_add_f32_e32 v6, v4, v5
	v_sub_f32_e32 v5, v69, v10
	v_exp_f32_e32 v5, v5
	v_exp_f32_e32 v38, v37
	v_sub_f32_e32 v37, v102, v10
	v_exp_f32_e32 v39, v37
	v_add_f32_e32 v7, v5, v6
	v_sub_f32_e32 v6, v70, v10
	v_exp_f32_e32 v6, v6
	v_sub_f32_e32 v37, v78, v10
	v_exp_f32_e32 v40, v37
	v_sub_f32_e32 v37, v79, v10
	v_add_f32_e32 v8, v6, v7
	v_sub_f32_e32 v7, v71, v10
	v_exp_f32_e32 v7, v7
	v_exp_f32_e32 v45, v37
	v_sub_f32_e32 v37, v80, v10
	v_exp_f32_e32 v48, v37
	v_add_f32_e32 v9, v7, v8
	v_sub_f32_e32 v8, v72, v10
	v_exp_f32_e32 v8, v8
	v_sub_f32_e32 v37, v81, v10
	v_exp_f32_e32 v51, v37
	v_sub_f32_e32 v37, v50, v10
	v_add_f32_e32 v34, v8, v9
	v_sub_f32_e32 v9, v99, v10
	v_exp_f32_e32 v9, v9
	v_exp_f32_e32 v37, v37
	v_sub_f32_e32 v41, v103, v10
	v_exp_f32_e32 v41, v41
	v_add_f32_e32 v34, v9, v34
	v_add_f32_e32 v34, v35, v34
	v_add_f32_e32 v34, v36, v34
	v_add_f32_e32 v34, v38, v34
	v_add_f32_e32 v34, v39, v34
	v_add_f32_e32 v34, v40, v34
	v_add_f32_e32 v34, v45, v34
	v_sub_f32_e32 v42, v104, v10
	v_add_f32_e32 v34, v48, v34
	v_exp_f32_e32 v43, v42
	v_sub_f32_e32 v42, v105, v10
	v_add_f32_e32 v34, v51, v34
	v_exp_f32_e32 v44, v42
	v_sub_f32_e32 v42, v54, v10
	v_add_f32_e32 v34, v37, v34
	v_exp_f32_e32 v47, v42
	v_sub_f32_e32 v42, v106, v10
	v_add_f32_e32 v34, v41, v34
	v_exp_f32_e32 v56, v42
	v_sub_f32_e32 v42, v107, v10
	v_add_f32_e32 v34, v43, v34
	v_exp_f32_e32 v62, v42
	v_sub_f32_e32 v42, v108, v10
	v_add_f32_e32 v34, v44, v34
	v_exp_f32_e32 v67, v42
	v_sub_f32_e32 v42, v109, v10
	v_add_f32_e32 v34, v47, v34
	v_exp_f32_e32 v42, v42
	v_sub_f32_e32 v46, v59, v10
	v_add_f32_e32 v34, v56, v34
	v_exp_f32_e32 v46, v46
	v_sub_f32_e32 v49, v60, v10
	v_add_f32_e32 v34, v62, v34
	v_exp_f32_e32 v50, v49
	v_sub_f32_e32 v49, v153, v10
	v_add_f32_e32 v34, v67, v34
	v_exp_f32_e32 v54, v49
	v_sub_f32_e32 v49, v154, v10
	v_add_f32_e32 v34, v42, v34
	v_exp_f32_e32 v59, v49
	v_sub_f32_e32 v49, v63, v10
	v_add_f32_e32 v34, v46, v34
	v_exp_f32_e32 v69, v49
	v_sub_f32_e32 v49, v155, v10
	v_add_f32_e32 v34, v50, v34
	v_exp_f32_e32 v72, v49
	v_sub_f32_e32 v49, v65, v10
	v_add_f32_e32 v34, v54, v34
	v_exp_f32_e32 v78, v49
	v_sub_f32_e32 v49, v156, v10
	v_add_f32_e32 v34, v59, v34
	v_exp_f32_e32 v49, v49
	v_sub_f32_e32 v60, v157, v10
	v_add_f32_e32 v34, v69, v34
	v_exp_f32_e32 v60, v60
	v_sub_f32_e32 v63, v158, v10
	v_add_f32_e32 v34, v72, v34
	v_exp_f32_e32 v65, v63
	v_sub_f32_e32 v63, v159, v10
	v_add_f32_e32 v34, v78, v34
	v_exp_f32_e32 v68, v63
	v_sub_f32_e32 v63, v160, v10
	v_add_f32_e32 v34, v49, v34
	v_exp_f32_e32 v71, v63
	v_sub_f32_e32 v63, v161, v10
	v_add_f32_e32 v34, v60, v34
	v_exp_f32_e32 v98, v63
	v_sub_f32_e32 v63, v162, v10
	v_add_f32_e32 v34, v65, v34
	v_exp_f32_e32 v103, v63
	v_sub_f32_e32 v63, v163, v10
	v_add_f32_e32 v34, v68, v34
	v_exp_f32_e32 v104, v63
	v_sub_f32_e32 v63, v164, v10
	v_add_f32_e32 v34, v71, v34
	v_exp_f32_e32 v63, v63
	v_sub_f32_e32 v70, v165, v10
	v_add_f32_e32 v34, v98, v34
	v_exp_f32_e32 v70, v70
	v_sub_f32_e32 v75, v166, v10
	v_add_f32_e32 v34, v103, v34
	v_exp_f32_e32 v75, v75
	v_sub_f32_e32 v79, v167, v10
	v_add_f32_e32 v34, v104, v34
	v_exp_f32_e32 v80, v79
	v_sub_f32_e32 v79, v168, v10
	v_add_f32_e32 v34, v63, v34
	v_exp_f32_e32 v101, v79
	v_sub_f32_e32 v77, v77, v10
	v_add_f32_e32 v34, v70, v34
	v_exp_f32_e32 v155, v77
	v_sub_f32_e32 v76, v76, v10
	v_add_f32_e32 v34, v75, v34
	v_exp_f32_e32 v159, v76
	v_sub_f32_e32 v74, v74, v10
	v_add_f32_e32 v34, v80, v34
	v_exp_f32_e32 v163, v74
	v_sub_f32_e32 v73, v73, v10
	v_add_f32_e32 v34, v101, v34
	v_exp_f32_e32 v74, v73
	v_sub_f32_e32 v66, v66, v10
	v_add_f32_e32 v34, v155, v34
	v_exp_f32_e32 v102, v66
	v_sub_f32_e32 v64, v64, v10
	v_add_f32_e32 v34, v159, v34
	v_exp_f32_e32 v153, v64
	v_sub_f32_e32 v61, v61, v10
	v_add_f32_e32 v34, v163, v34
	v_exp_f32_e32 v154, v61
	v_sub_f32_e32 v58, v58, v10
	v_add_f32_e32 v34, v74, v34
	v_exp_f32_e32 v157, v58
	v_sub_f32_e32 v57, v57, v10
	v_add_f32_e32 v34, v102, v34
	v_exp_f32_e32 v166, v57
	v_sub_f32_e32 v55, v55, v10
	v_add_f32_e32 v34, v153, v34
	v_exp_f32_e32 v167, v55
	v_sub_f32_e32 v53, v53, v10
	v_add_f32_e32 v34, v154, v34
	v_exp_f32_e32 v168, v53
	v_sub_f32_e32 v52, v52, v10
	v_add_f32_e32 v34, v157, v34
	v_exp_f32_e32 v109, v52
	v_sub_f32_e32 v33, v33, v10
	v_add_f32_e32 v34, v166, v34
	v_exp_f32_e32 v156, v33
	v_sub_f32_e32 v32, v32, v10
	v_add_f32_e32 v34, v167, v34
	v_exp_f32_e32 v158, v32
	v_sub_f32_e32 v31, v31, v10
	v_add_f32_e32 v34, v168, v34
	v_exp_f32_e32 v160, v31
	v_sub_f32_e32 v30, v30, v10
	v_add_f32_e32 v34, v109, v34
	v_exp_f32_e32 v161, v30
	v_sub_f32_e32 v29, v29, v10
	v_add_f32_e32 v33, v156, v34
	v_exp_f32_e32 v162, v29
	v_sub_f32_e32 v28, v28, v10
	v_add_f32_e32 v32, v158, v33
	v_exp_f32_e32 v164, v28
	v_sub_f32_e32 v27, v27, v10
	v_add_f32_e32 v31, v160, v32
	v_exp_f32_e32 v165, v27
	v_sub_f32_e32 v26, v26, v10
	v_add_f32_e32 v30, v161, v31
	v_exp_f32_e32 v73, v26
	v_sub_f32_e32 v25, v25, v10
	v_add_f32_e32 v29, v162, v30
	v_exp_f32_e32 v76, v25
	v_sub_f32_e32 v24, v24, v10
	v_add_f32_e32 v28, v164, v29
	v_exp_f32_e32 v77, v24
	v_sub_f32_e32 v23, v23, v10
	v_add_f32_e32 v27, v165, v28
	v_exp_f32_e32 v79, v23
	v_sub_f32_e32 v22, v22, v10
	v_add_f32_e32 v26, v73, v27
	v_exp_f32_e32 v81, v22
	v_sub_f32_e32 v21, v21, v10
	v_add_f32_e32 v25, v76, v26
	v_exp_f32_e32 v99, v21
	v_sub_f32_e32 v20, v20, v10
	v_add_f32_e32 v24, v77, v25
	v_exp_f32_e32 v100, v20
	v_sub_f32_e32 v19, v19, v10
	v_add_u32_e32 v105, v130, v131
	v_add_f32_e32 v23, v79, v24
	v_exp_f32_e32 v108, v19
	v_sub_f32_e32 v18, v18, v10
	v_cvt_pk_bf16_f32 v2, v2, v3
	v_cvt_pk_bf16_f32 v3, v4, v5
	v_cvt_pk_bf16_f32 v4, v6, v7
	v_cvt_pk_bf16_f32 v5, v8, v9
	ds_read_b128 v[6:9], v105 offset:36864
	v_add_f32_e32 v22, v81, v23
	v_exp_f32_e32 v52, v18
	v_sub_f32_e32 v17, v17, v10
	v_add_f32_e32 v21, v99, v22
	v_exp_f32_e32 v53, v17
	v_sub_f32_e32 v16, v16, v10
	v_add_f32_e32 v20, v100, v21
	v_exp_f32_e32 v55, v16
	v_sub_f32_e32 v15, v15, v10
	v_add_f32_e32 v19, v108, v20
	v_exp_f32_e32 v57, v15
	v_sub_f32_e32 v14, v14, v10
	v_add_f32_e32 v18, v52, v19
	v_exp_f32_e32 v58, v14
	v_sub_f32_e32 v13, v13, v10
	v_add_f32_e32 v17, v53, v18
	v_exp_f32_e32 v61, v13
	v_sub_f32_e32 v12, v12, v10
	v_add_f32_e32 v16, v55, v17
	v_exp_f32_e32 v64, v12
	v_sub_f32_e32 v11, v11, v10
	v_add_f32_e32 v15, v57, v16
	v_exp_f32_e32 v66, v11
	v_add_u32_e32 v106, v130, v132
	v_add_f32_e32 v14, v58, v15
	s_waitcnt lgkmcnt(0)
	v_mfma_f32_32x32x16_bf16 v[18:33], v[6:9], v[2:5], 0
	ds_read_b128 v[6:9], v106 offset:36864
	v_cvt_pk_bf16_f32 v170, v35, v36
	v_cvt_pk_bf16_f32 v171, v38, v39
	v_cvt_pk_bf16_f32 v172, v40, v45
	v_cvt_pk_bf16_f32 v173, v48, v51
	ds_read_b128 v[174:177], v105 offset:36896
	v_add_f32_e32 v13, v61, v14
	v_add_f32_e32 v12, v64, v13
	v_add_f32_e32 v11, v66, v12
	ds_bpermute_b32 v12, v129, v11
	v_fma_f32 v10, v149, s94, -v10
	v_exp_f32_e32 v10, v10
	s_waitcnt lgkmcnt(1)
	v_mfma_f32_32x32x16_bf16 v[18:33], v[174:177], v[170:173], v[18:33]
	s_waitcnt lgkmcnt(0)
	v_add_f32_e32 v11, v11, v12
	ds_read_b128 v[174:177], v106 offset:36896
	v_add_f32_e32 v34, v10, v11
	v_add_u32_e32 v107, v133, v131
	v_cvt_pk_bf16_f32 v36, v37, v41
	v_cvt_pk_bf16_f32 v37, v43, v44
	v_cvt_pk_bf16_f32 v38, v47, v56
	v_mfma_f32_32x32x16_bf16 v[2:17], v[6:9], v[2:5], 0
	v_cvt_pk_bf16_f32 v39, v62, v67
	v_add_u32_e32 v106, v133, v132
	v_add_u32_e32 v105, v134, v131
	v_div_scale_f32 v35, vcc, v34, v34, 1.0
	s_waitcnt lgkmcnt(0)
	v_mfma_f32_32x32x16_bf16 v[2:17], v[174:177], v[170:173], v[2:17]
	ds_read_b128 v[178:181], v107 offset:36864
	ds_read_b128 v[182:185], v106 offset:36864
	ds_read_b128 v[186:189], v107 offset:36896
	s_waitcnt lgkmcnt(2)
	v_mfma_f32_32x32x16_bf16 v[18:33], v[178:181], v[36:39], v[18:33]
	ds_read_b128 v[190:193], v106 offset:36896
	s_waitcnt lgkmcnt(2)
	v_mfma_f32_32x32x16_bf16 v[2:17], v[182:185], v[36:39], v[2:17]
	v_cvt_pk_bf16_f32 v36, v42, v46
	v_cvt_pk_bf16_f32 v37, v50, v54
	v_cvt_pk_bf16_f32 v38, v59, v69
	v_cvt_pk_bf16_f32 v39, v72, v78
	ds_read_b128 v[178:181], v105 offset:36864
	s_waitcnt lgkmcnt(2)
	v_mfma_f32_32x32x16_bf16 v[18:33], v[186:189], v[36:39], v[18:33]
	v_add_u32_e32 v194, v134, v132
	ds_read_b128 v[182:185], v194 offset:36864
	s_waitcnt lgkmcnt(2)
	v_mfma_f32_32x32x16_bf16 v[2:17], v[190:193], v[36:39], v[2:17]
	v_cvt_pk_bf16_f32 v36, v49, v60
	v_cvt_pk_bf16_f32 v37, v65, v68
	v_cvt_pk_bf16_f32 v38, v71, v98
	v_cvt_pk_bf16_f32 v39, v103, v104
	v_add_u32_e32 v104, v134, v132
	v_add_u32_e32 v103, v135, v131
	ds_read_b128 v[186:189], v105 offset:36896
	s_waitcnt lgkmcnt(2)
	v_mfma_f32_32x32x16_bf16 v[18:33], v[178:181], v[36:39], v[18:33]
	v_or_b32_e32 v98, s88, v152
	ds_read_b128 v[190:193], v104 offset:36896
	s_waitcnt lgkmcnt(2)
	v_mfma_f32_32x32x16_bf16 v[2:17], v[182:185], v[36:39], v[2:17]
	v_cvt_pk_bf16_f32 v36, v63, v70
	v_cvt_pk_bf16_f32 v37, v75, v80
	v_cvt_pk_bf16_f32 v38, v101, v155
	v_cvt_pk_bf16_f32 v39, v159, v163
	v_add_u32_e32 v101, v136, v131
	ds_read_b128 v[178:181], v103 offset:36864
	s_waitcnt lgkmcnt(2)
	v_mfma_f32_32x32x16_bf16 v[18:33], v[186:189], v[36:39], v[18:33]
	v_add_u32_e32 v202, v135, v132
	ds_read_b128 v[182:185], v202 offset:36864
	s_waitcnt lgkmcnt(2)
	v_mfma_f32_32x32x16_bf16 v[2:17], v[190:193], v[36:39], v[2:17]
	v_cvt_pk_bf16_f32 v36, v74, v102
	v_cvt_pk_bf16_f32 v37, v153, v154
	v_cvt_pk_bf16_f32 v38, v157, v166
	v_cvt_pk_bf16_f32 v39, v167, v168
	v_add_u32_e32 v102, v135, v132
	ds_read_b128 v[186:189], v103 offset:36896
	s_waitcnt lgkmcnt(2)
	v_mfma_f32_32x32x16_bf16 v[18:33], v[178:181], v[36:39], v[18:33]
	ds_read_b128 v[190:193], v102 offset:36896
	s_waitcnt lgkmcnt(2)
	v_mfma_f32_32x32x16_bf16 v[2:17], v[182:185], v[36:39], v[2:17]
	v_cvt_pk_bf16_f32 v36, v109, v156
	v_cvt_pk_bf16_f32 v37, v158, v160
	v_cvt_pk_bf16_f32 v38, v161, v162
	v_cvt_pk_bf16_f32 v39, v164, v165
	ds_read_b128 v[178:181], v101 offset:36864
	s_waitcnt lgkmcnt(2)
	v_mfma_f32_32x32x16_bf16 v[18:33], v[186:189], v[36:39], v[18:33]
	v_add_u32_e32 v203, v136, v132
	ds_read_b128 v[182:185], v203 offset:36864
	s_waitcnt lgkmcnt(2)
	v_mfma_f32_32x32x16_bf16 v[2:17], v[190:193], v[36:39], v[2:17]
	v_cvt_pk_bf16_f32 v36, v73, v76
	v_cvt_pk_bf16_f32 v37, v77, v79
	v_cvt_pk_bf16_f32 v38, v81, v99
	v_cvt_pk_bf16_f32 v39, v100, v108
	v_add_u32_e32 v100, v136, v132
	v_mov_b32_e32 v99, s89
	ds_read_b128 v[186:189], v101 offset:36896
	s_waitcnt lgkmcnt(2)
	v_mfma_f32_32x32x16_bf16 v[18:33], v[178:181], v[36:39], v[18:33]
	ds_read_b128 v[190:193], v100 offset:36896
	s_waitcnt lgkmcnt(2)
	v_mfma_f32_32x32x16_bf16 v[2:17], v[182:185], v[36:39], v[2:17]
	v_cvt_pk_bf16_f32 v36, v52, v53
	v_cvt_pk_bf16_f32 v37, v55, v57
	v_cvt_pk_bf16_f32 v38, v58, v61
	v_cvt_pk_bf16_f32 v39, v64, v66
	s_nop 0
	s_waitcnt lgkmcnt(1)
	v_mfma_f32_32x32x16_bf16 v[18:33], v[186:189], v[36:39], v[18:33]
	s_waitcnt lgkmcnt(0)
	v_mfma_f32_32x32x16_bf16 v[2:17], v[190:193], v[36:39], v[2:17]
	v_rcp_f32_e32 v36, v35
	s_nop 0
	v_fma_f32 v37, -v35, v36, 1.0
	v_fmac_f32_e32 v36, v37, v36
	v_div_scale_f32 v37, vcc, 1.0, v34, 1.0
	v_mul_f32_e32 v38, v37, v36
	v_fma_f32 v39, -v35, v38, v37
	v_fmac_f32_e32 v38, v39, v36
	v_fma_f32 v35, -v35, v38, v37
	v_div_fmas_f32 v35, v35, v36, v38
	v_div_fixup_f32 v36, v35, v34, 1.0
	v_lshlrev_b64 v[34:35], 11, v[98:99]
	v_bfe_u32 v204, v0, 5, 1
	v_lshl_add_u64 v[34:35], v[126:127], 0, v[34:35]
	v_lshlrev_b32_e32 v204, 3, v204
	v_mov_b32_e32 v205, 0
	v_mul_f32_e32 v18, v18, v36
	v_mul_f32_e32 v19, v19, v36
	v_cvt_pk_bf16_f32 v18, v18, v19
	v_mul_f32_e32 v19, v20, v36
	v_mul_f32_e32 v20, v21, v36
	v_cvt_pk_bf16_f32 v19, v19, v20
	v_mul_f32_e32 v20, v22, v36
	v_mul_f32_e32 v21, v23, v36
	v_cvt_pk_bf16_f32 v20, v20, v21
	v_mul_f32_e32 v21, v24, v36
	v_mul_f32_e32 v22, v25, v36
	v_cvt_pk_bf16_f32 v21, v21, v22
	v_lshl_add_u64 v[34:35], v[34:35], 0, v[204:205]
	v_mul_f32_e32 v26, v26, v36
	v_mul_f32_e32 v27, v27, v36
	v_cvt_pk_bf16_f32 v26, v26, v27
	v_mul_f32_e32 v27, v28, v36
	v_mul_f32_e32 v28, v29, v36
	v_cvt_pk_bf16_f32 v27, v27, v28
	v_mul_f32_e32 v28, v30, v36
	v_mul_f32_e32 v29, v31, v36
	v_cvt_pk_bf16_f32 v28, v28, v29
	v_mul_f32_e32 v29, v32, v36
	v_mul_f32_e32 v30, v33, v36
	v_cvt_pk_bf16_f32 v29, v29, v30
	v_permlane32_swap_b32 v18, v20
	v_permlane32_swap_b32 v19, v21
	global_store_dwordx4 v[34:35], v[18:21], off
	v_permlane32_swap_b32 v26, v28
	v_permlane32_swap_b32 v27, v29
	global_store_dwordx4 v[34:35], v[26:29], off offset:32
	v_mul_f32_e32 v2, v2, v36
	v_mul_f32_e32 v3, v3, v36
	v_cvt_pk_bf16_f32 v2, v2, v3
	v_mul_f32_e32 v3, v4, v36
	v_mul_f32_e32 v4, v5, v36
	v_cvt_pk_bf16_f32 v3, v3, v4
	v_mul_f32_e32 v4, v6, v36
	v_mul_f32_e32 v5, v7, v36
	v_cvt_pk_bf16_f32 v4, v4, v5
	v_mul_f32_e32 v5, v8, v36
	v_mul_f32_e32 v6, v9, v36
	v_cvt_pk_bf16_f32 v5, v5, v6
	v_mul_f32_e32 v10, v10, v36
	v_mul_f32_e32 v11, v11, v36
	v_cvt_pk_bf16_f32 v10, v10, v11
	v_mul_f32_e32 v11, v12, v36
	v_mul_f32_e32 v12, v13, v36
	v_cvt_pk_bf16_f32 v11, v11, v12
	v_mul_f32_e32 v12, v14, v36
	v_mul_f32_e32 v13, v15, v36
	v_cvt_pk_bf16_f32 v12, v12, v13
	v_mul_f32_e32 v13, v16, v36
	v_mul_f32_e32 v14, v17, v36
	v_cvt_pk_bf16_f32 v13, v13, v14
	v_permlane32_swap_b32 v2, v4
	v_permlane32_swap_b32 v3, v5
	global_store_dwordx4 v[34:35], v[2:5], off offset:64
	v_permlane32_swap_b32 v10, v12
	v_permlane32_swap_b32 v11, v13
	global_store_dwordx4 v[34:35], v[10:13], off offset:96
	ds_read_b128 v[178:181], v143
	ds_read_b128 v[182:185], v143 offset:32
	ds_read_b128 v[186:189], v143 offset:64
	s_waitcnt lgkmcnt(2)
	v_mfma_f32_32x32x16_bf16 v[66:81], v[178:181], v[94:97], 0
	v_or_b32_e32 v98, s87, v150
	v_or_b32_e32 v98, s88, v98
	ds_read_b128 v[190:193], v143 offset:96
	s_waitcnt lgkmcnt(2)
	v_mfma_f32_32x32x16_bf16 v[66:81], v[182:185], v[90:93], v[66:81]
	ds_read_b128 v[178:181], v144
	s_waitcnt lgkmcnt(2)
	v_mfma_f32_32x32x16_bf16 v[66:81], v[186:189], v[86:89], v[66:81]
	ds_read_b128 v[182:185], v144 offset:32
	s_waitcnt lgkmcnt(2)
	v_mfma_f32_32x32x16_bf16 v[66:81], v[190:193], v[82:85], v[66:81]
	ds_read_b128 v[186:189], v144 offset:64
	s_waitcnt lgkmcnt(2)
	v_mfma_f32_32x32x16_bf16 v[34:49], v[178:181], v[94:97], 0
	s_nop 6
	s_nop 0
	s_nop 0
	v_cndmask_b32_e64 v66, v245, v66, s[48:49]
	v_cndmask_b32_e64 v68, v245, v68, s[52:53]
	v_cndmask_b32_e64 v69, v245, v69, s[54:55]
	v_cndmask_b32_e64 v70, v245, v70, s[56:57]
	v_cndmask_b32_e64 v71, v245, v71, s[58:59]
	v_cndmask_b32_e64 v72, v245, v72, s[60:61]
	ds_read_b128 v[190:193], v144 offset:96
	s_waitcnt lgkmcnt(2)
	v_mfma_f32_32x32x16_bf16 v[34:49], v[182:185], v[90:93], v[34:49]
	v_cndmask_b32_e64 v73, v245, v73, s[62:63]
	v_cndmask_b32_e64 v74, v245, v74, s[64:65]
	v_cndmask_b32_e64 v75, v245, v75, s[66:67]
	v_cndmask_b32_e64 v76, v245, v76, s[68:69]
	v_cndmask_b32_e64 v77, v245, v77, s[70:71]
	v_cndmask_b32_e64 v78, v245, v78, s[72:73]
	v_cndmask_b32_e64 v79, v245, v79, s[74:75]
	ds_read_b128 v[178:181], v145
	s_waitcnt lgkmcnt(2)
	v_mfma_f32_32x32x16_bf16 v[34:49], v[186:189], v[86:89], v[34:49]
	v_cndmask_b32_e64 v80, v245, v80, s[76:77]
	v_cndmask_b32_e64 v81, v245, v81, s[78:79]
	ds_read_b128 v[182:185], v145 offset:32
	s_waitcnt lgkmcnt(2)
	v_mfma_f32_32x32x16_bf16 v[34:49], v[190:193], v[82:85], v[34:49]
	ds_read_b128 v[186:189], v145 offset:64
	s_waitcnt lgkmcnt(2)
	v_mfma_f32_32x32x16_bf16 v[18:33], v[178:181], v[94:97], 0
	s_nop 6
	s_nop 1
	v_cndmask_b32_e64 v42, v42, v245, s[80:81]
	ds_read_b128 v[190:193], v145 offset:96
	s_waitcnt lgkmcnt(2)
	v_mfma_f32_32x32x16_bf16 v[18:33], v[182:185], v[90:93], v[18:33]
	ds_read_b128 v[178:181], v146
	s_waitcnt lgkmcnt(2)
	v_mfma_f32_32x32x16_bf16 v[18:33], v[186:189], v[86:89], v[18:33]
	ds_read_b128 v[182:185], v146 offset:32
	s_waitcnt lgkmcnt(2)
	v_mfma_f32_32x32x16_bf16 v[18:33], v[190:193], v[82:85], v[18:33]
	ds_read_b128 v[186:189], v146 offset:64
	s_waitcnt lgkmcnt(2)
	v_mfma_f32_32x32x16_bf16 v[2:17], v[178:181], v[94:97], 0
	s_nop 7
	s_nop 0
	v_cndmask_b32_e64 v108, v18, v245, s[80:81]
	v_cndmask_b32_e64 v109, v19, v245, s[80:81]
	v_cndmask_b32_e64 v150, v20, v245, s[80:81]
	v_cndmask_b32_e64 v156, v26, v245, s[80:81]
	v_cndmask_b32_e64 v157, v27, v245, s[80:81]
	v_cndmask_b32_e64 v158, v28, v245, s[80:81]
	v_cndmask_b32_e64 v159, v29, v245, s[80:81]
	ds_read_b128 v[190:193], v146 offset:96
	s_waitcnt lgkmcnt(2)
	v_mfma_f32_32x32x16_bf16 v[2:17], v[182:185], v[90:93], v[2:17]
	v_cndmask_b32_e64 v160, v30, v245, s[80:81]
	v_cndmask_b32_e64 v161, v31, v245, s[80:81]
	v_cndmask_b32_e64 v162, v32, v245, s[80:81]
	v_cndmask_b32_e64 v163, v33, v245, s[80:81]
	ds_read_b128 v[178:181], v147
	s_waitcnt lgkmcnt(2)
	v_mfma_f32_32x32x16_bf16 v[2:17], v[186:189], v[86:89], v[2:17]
	ds_read_b128 v[182:185], v147 offset:32
	s_waitcnt lgkmcnt(2)
	v_mfma_f32_32x32x16_bf16 v[2:17], v[190:193], v[82:85], v[2:17]
	ds_read_b128 v[186:189], v147 offset:64
	s_waitcnt lgkmcnt(2)
	v_mfma_f32_32x32x16_bf16 v[50:65], v[178:181], v[94:97], 0
	v_cndmask_b32_e64 v94, v46, v245, s[80:81]
	v_cndmask_b32_e64 v95, v47, v245, s[80:81]
	v_cndmask_b32_e64 v96, v48, v245, s[80:81]
	v_cndmask_b32_e64 v97, v49, v245, s[80:81]
	ds_read_b128 v[190:193], v147 offset:96
	s_waitcnt lgkmcnt(2)
	v_mfma_f32_32x32x16_bf16 v[50:65], v[182:185], v[90:93], v[50:65]
	v_cndmask_b32_e64 v152, v22, v245, s[80:81]
	v_cndmask_b32_e64 v153, v23, v245, s[80:81]
	v_cndmask_b32_e64 v154, v24, v245, s[80:81]
	v_cndmask_b32_e64 v155, v25, v245, s[80:81]
	s_waitcnt lgkmcnt(1)
	v_mfma_f32_32x32x16_bf16 v[50:65], v[186:189], v[86:89], v[50:65]
	v_cndmask_b32_e64 v90, v41, v245, s[80:81]
	v_cndmask_b32_e64 v91, v43, v245, s[80:81]
	v_cndmask_b32_e64 v92, v44, v245, s[80:81]
	v_cndmask_b32_e64 v93, v45, v245, s[80:81]
	s_waitcnt lgkmcnt(0)
	v_mfma_f32_32x32x16_bf16 v[50:65], v[190:193], v[82:85], v[50:65]
	v_cndmask_b32_e64 v82, v245, v67, s[50:51]
	v_max3_f32 v67, v151, v66, v82
	v_max3_f32 v67, v67, v68, v69
	v_max3_f32 v67, v67, v70, v71
	v_max3_f32 v67, v67, v72, v73
	v_max3_f32 v67, v67, v74, v75
	v_max3_f32 v67, v67, v76, v77
	v_max3_f32 v67, v67, v78, v79
	v_max3_f32 v67, v67, v80, v81
	v_cndmask_b32_e64 v83, v34, v245, s[80:81]
	v_cndmask_b32_e64 v84, v35, v245, s[80:81]
	v_max3_f32 v34, v67, v83, v84
	v_cndmask_b32_e64 v85, v36, v245, s[80:81]
	v_cndmask_b32_e64 v86, v37, v245, s[80:81]
	v_max3_f32 v34, v34, v85, v86
	v_cndmask_b32_e64 v87, v38, v245, s[80:81]
	v_cndmask_b32_e64 v88, v39, v245, s[80:81]
	v_max3_f32 v34, v34, v87, v88
	v_cndmask_b32_e64 v89, v40, v245, s[80:81]
	v_max3_f32 v34, v34, v89, v90
	v_max3_f32 v34, v34, v42, v91
	v_max3_f32 v34, v34, v92, v93
	v_max3_f32 v34, v34, v94, v95
	v_max3_f32 v34, v34, v96, v97
	v_max3_f32 v18, v34, v108, v109
	v_cndmask_b32_e64 v151, v21, v245, s[80:81]
	v_max3_f32 v18, v18, v150, v151
	v_max3_f32 v18, v18, v152, v153
	v_max3_f32 v18, v18, v154, v155
	v_max3_f32 v18, v18, v156, v157
	v_max3_f32 v18, v18, v158, v159
	v_max3_f32 v18, v18, v160, v161
	v_max3_f32 v18, v18, v162, v163
	v_max3_f32 v18, v18, v2, v3
	v_max3_f32 v18, v18, v4, v5
	v_max3_f32 v18, v18, v6, v7
	v_max3_f32 v18, v18, v8, v9
	v_max3_f32 v18, v18, v10, v11
	v_max3_f32 v18, v18, v12, v13
	v_max3_f32 v18, v18, v14, v15
	v_max3_f32 v18, v18, v16, v17
	v_cndmask_b32_e64 v67, v50, v245, s[12:13]
	v_cndmask_b32_e64 v50, v245, v51, s[46:47]
	v_max3_f32 v18, v18, v67, v50
	v_cndmask_b32_e64 v49, v52, v245, s[16:17]
	v_cndmask_b32_e64 v48, v53, v245, s[18:19]
	v_max3_f32 v18, v18, v49, v48
	v_cndmask_b32_e64 v47, v54, v245, s[20:21]
	v_cndmask_b32_e64 v45, v55, v245, s[22:23]
	v_max3_f32 v18, v18, v47, v45
	v_cndmask_b32_e64 v43, v56, v245, s[24:25]
	v_cndmask_b32_e64 v40, v57, v245, s[26:27]
	v_max3_f32 v18, v18, v43, v40
	v_cndmask_b32_e64 v34, v58, v245, s[28:29]
	v_cndmask_b32_e64 v33, v59, v245, s[30:31]
	v_max3_f32 v18, v18, v34, v33
	v_cndmask_b32_e64 v32, v60, v245, s[34:35]
	v_cndmask_b32_e64 v31, v61, v245, s[36:37]
	v_max3_f32 v18, v18, v32, v31
	v_cndmask_b32_e64 v30, v62, v245, s[38:39]
	v_cndmask_b32_e64 v29, v63, v245, s[42:43]
	v_max3_f32 v18, v18, v30, v29
	v_cndmask_b32_e64 v28, v64, v245, s[44:45]
	v_cndmask_b32_e64 v27, v65, v245, s[0:1]
	v_max3_f32 v18, v18, v28, v27
	v_mov_b32_e32 v19, v18
	v_mov_b32_e32 v206, v18
	s_nop 1
	v_permlane32_swap_b32 v19, v206
	v_max_f32_e32 v26, v19, v206
	v_sub_f32_e32 v18, v66, v26
	v_exp_f32_e32 v18, v18
	v_sub_f32_e32 v19, v82, v26
	v_exp_f32_e32 v19, v19
	v_sub_f32_e32 v38, v76, v26
	v_add_f32_e32 v20, 0, v18
	v_exp_f32_e32 v38, v38
	v_add_f32_e32 v21, v19, v20
	v_sub_f32_e32 v20, v68, v26
	v_exp_f32_e32 v20, v20
	v_sub_f32_e32 v39, v77, v26
	v_exp_f32_e32 v39, v39
	v_sub_f32_e32 v41, v78, v26
	v_add_f32_e32 v22, v20, v21
	v_sub_f32_e32 v21, v69, v26
	v_exp_f32_e32 v21, v21
	v_exp_f32_e32 v44, v41
	v_sub_f32_e32 v41, v79, v26
	v_exp_f32_e32 v54, v41
	v_add_f32_e32 v23, v21, v22
	v_sub_f32_e32 v22, v70, v26
	v_exp_f32_e32 v22, v22
	v_sub_f32_e32 v41, v80, v26
	v_exp_f32_e32 v58, v41
	v_sub_f32_e32 v41, v81, v26
	v_add_f32_e32 v24, v22, v23
	v_sub_f32_e32 v23, v71, v26
	v_exp_f32_e32 v23, v23
	v_exp_f32_e32 v60, v41
	v_sub_f32_e32 v53, v87, v26
	v_exp_f32_e32 v56, v53
	v_add_f32_e32 v25, v23, v24
	v_sub_f32_e32 v24, v72, v26
	v_exp_f32_e32 v24, v24
	v_sub_f32_e32 v53, v88, v26
	v_exp_f32_e32 v63, v53
	v_sub_f32_e32 v53, v89, v26
	v_add_f32_e32 v35, v24, v25
	v_sub_f32_e32 v25, v73, v26
	v_exp_f32_e32 v25, v25
	v_exp_f32_e32 v70, v53
	v_sub_f32_e32 v53, v90, v26
	v_sub_f32_e32 v42, v42, v26
	v_add_f32_e32 v36, v25, v35
	v_sub_f32_e32 v35, v74, v26
	v_exp_f32_e32 v35, v35
	v_exp_f32_e32 v42, v42
	v_sub_f32_e32 v55, v92, v26
	v_exp_f32_e32 v57, v55
	v_add_f32_e32 v37, v35, v36
	v_sub_f32_e32 v36, v75, v26
	v_exp_f32_e32 v36, v36
	v_exp_f32_e32 v75, v53
	v_sub_f32_e32 v53, v91, v26
	v_exp_f32_e32 v53, v53
	v_add_f32_e32 v37, v36, v37
	v_add_f32_e32 v37, v38, v37
	v_add_f32_e32 v37, v39, v37
	v_add_f32_e32 v37, v44, v37
	v_add_f32_e32 v37, v54, v37
	v_add_f32_e32 v37, v58, v37
	v_add_f32_e32 v41, v60, v37
	v_sub_f32_e32 v37, v83, v26
	v_exp_f32_e32 v37, v37
	v_sub_f32_e32 v55, v93, v26
	v_exp_f32_e32 v59, v55
	v_sub_f32_e32 v55, v94, v26
	v_add_f32_e32 v46, v37, v41
	v_sub_f32_e32 v41, v84, v26
	v_exp_f32_e32 v41, v41
	v_exp_f32_e32 v66, v55
	v_sub_f32_e32 v55, v95, v26
	v_exp_f32_e32 v78, v55
	v_add_f32_e32 v51, v41, v46
	v_sub_f32_e32 v46, v85, v26
	v_exp_f32_e32 v46, v46
	v_sub_f32_e32 v55, v96, v26
	v_exp_f32_e32 v82, v55
	v_sub_f32_e32 v55, v97, v26
	v_add_f32_e32 v52, v46, v51
	v_sub_f32_e32 v51, v86, v26
	v_exp_f32_e32 v51, v51
	v_exp_f32_e32 v85, v55
	v_sub_f32_e32 v55, v108, v26
	v_exp_f32_e32 v55, v55
	v_add_f32_e32 v52, v51, v52
	v_add_f32_e32 v52, v56, v52
	v_add_f32_e32 v52, v63, v52
	v_add_f32_e32 v52, v70, v52
	v_add_f32_e32 v52, v75, v52
	v_add_f32_e32 v52, v42, v52
	v_add_f32_e32 v52, v53, v52
	v_add_f32_e32 v52, v57, v52
	v_add_f32_e32 v52, v59, v52
	v_add_f32_e32 v52, v66, v52
	v_sub_f32_e32 v61, v109, v26
	v_add_f32_e32 v52, v78, v52
	v_exp_f32_e32 v62, v61
	v_sub_f32_e32 v61, v150, v26
	v_add_f32_e32 v52, v82, v52
	v_exp_f32_e32 v68, v61
	v_sub_f32_e32 v61, v151, v26
	v_add_f32_e32 v52, v85, v52
	v_exp_f32_e32 v74, v61
	v_sub_f32_e32 v61, v152, v26
	v_add_f32_e32 v52, v55, v52
	v_exp_f32_e32 v80, v61
	v_sub_f32_e32 v61, v153, v26
	v_add_f32_e32 v52, v62, v52
	v_exp_f32_e32 v88, v61
	v_sub_f32_e32 v61, v154, v26
	v_add_f32_e32 v52, v68, v52
	v_exp_f32_e32 v94, v61
	v_sub_f32_e32 v61, v155, v26
	v_add_f32_e32 v52, v74, v52
	v_exp_f32_e32 v109, v61
	v_sub_f32_e32 v61, v156, v26
	v_add_f32_e32 v52, v80, v52
	v_exp_f32_e32 v64, v61
	v_sub_f32_e32 v61, v157, v26
	v_add_f32_e32 v52, v88, v52
	v_exp_f32_e32 v77, v61
	v_sub_f32_e32 v61, v158, v26
	v_add_f32_e32 v52, v94, v52
	v_exp_f32_e32 v81, v61
	v_sub_f32_e32 v61, v159, v26
	v_add_f32_e32 v52, v109, v52
	v_exp_f32_e32 v83, v61
	v_sub_f32_e32 v61, v160, v26
	v_add_f32_e32 v52, v64, v52
	v_exp_f32_e32 v90, v61
	v_sub_f32_e32 v61, v161, v26
	v_add_f32_e32 v52, v77, v52
	v_exp_f32_e32 v150, v61
	v_sub_f32_e32 v61, v162, v26
	v_add_f32_e32 v52, v81, v52
	v_exp_f32_e32 v152, v61
	v_sub_f32_e32 v61, v163, v26
	v_add_f32_e32 v52, v83, v52
	v_exp_f32_e32 v153, v61
	v_sub_f32_e32 v2, v2, v26
	v_add_f32_e32 v52, v90, v52
	v_exp_f32_e32 v79, v2
	v_sub_f32_e32 v3, v3, v26
	v_add_f32_e32 v52, v150, v52
	v_exp_f32_e32 v86, v3
	v_sub_f32_e32 v3, v4, v26
	v_add_f32_e32 v52, v152, v52
	v_exp_f32_e32 v92, v3
	v_sub_f32_e32 v3, v5, v26
	v_add_f32_e32 v52, v153, v52
	v_exp_f32_e32 v97, v3
	v_sub_f32_e32 v3, v6, v26
	v_add_f32_e32 v2, v79, v52
	v_exp_f32_e32 v151, v3
	v_sub_f32_e32 v3, v7, v26
	v_add_f32_e32 v2, v86, v2
	v_exp_f32_e32 v154, v3
	v_sub_f32_e32 v3, v8, v26
	v_add_f32_e32 v2, v92, v2
	v_exp_f32_e32 v155, v3
	v_sub_f32_e32 v3, v9, v26
	v_add_f32_e32 v2, v97, v2
	v_exp_f32_e32 v156, v3
	v_sub_f32_e32 v3, v10, v26
	v_add_f32_e32 v2, v151, v2
	v_exp_f32_e32 v84, v3
	v_sub_f32_e32 v3, v11, v26
	v_add_f32_e32 v2, v154, v2
	v_exp_f32_e32 v87, v3
	v_sub_f32_e32 v3, v12, v26
	v_add_f32_e32 v2, v155, v2
	v_exp_f32_e32 v89, v3
	v_sub_f32_e32 v3, v13, v26
	v_add_f32_e32 v2, v156, v2
	v_exp_f32_e32 v91, v3
	v_sub_f32_e32 v3, v14, v26
	v_add_f32_e32 v2, v84, v2
	v_exp_f32_e32 v93, v3
	v_sub_f32_e32 v3, v15, v26
	v_add_f32_e32 v2, v87, v2
	v_exp_f32_e32 v95, v3
	v_sub_f32_e32 v3, v16, v26
	v_add_f32_e32 v2, v89, v2
	v_exp_f32_e32 v96, v3
	v_sub_f32_e32 v3, v17, v26
	v_add_f32_e32 v2, v91, v2
	v_exp_f32_e32 v108, v3
	v_sub_f32_e32 v3, v67, v26
	v_add_f32_e32 v2, v93, v2
	v_exp_f32_e32 v61, v3
	v_sub_f32_e32 v3, v50, v26
	v_add_f32_e32 v2, v95, v2
	v_exp_f32_e32 v65, v3
	v_sub_f32_e32 v3, v49, v26
	v_add_f32_e32 v2, v96, v2
	v_exp_f32_e32 v67, v3
	v_sub_f32_e32 v3, v48, v26
	v_add_f32_e32 v2, v108, v2
	v_exp_f32_e32 v69, v3
	v_sub_f32_e32 v3, v47, v26
	v_add_f32_e32 v2, v61, v2
	v_exp_f32_e32 v71, v3
	v_sub_f32_e32 v3, v45, v26
	v_add_f32_e32 v2, v65, v2
	v_exp_f32_e32 v72, v3
	v_sub_f32_e32 v3, v43, v26
	v_add_f32_e32 v2, v67, v2
	v_exp_f32_e32 v73, v3
	v_sub_f32_e32 v3, v40, v26
	v_add_f32_e32 v2, v69, v2
	v_exp_f32_e32 v76, v3
	v_sub_f32_e32 v3, v34, v26
	v_add_f32_e32 v2, v71, v2
	v_exp_f32_e32 v40, v3
	v_sub_f32_e32 v3, v33, v26
	v_add_f32_e32 v2, v72, v2
	v_exp_f32_e32 v43, v3
	v_sub_f32_e32 v3, v32, v26
	v_add_f32_e32 v2, v73, v2
	v_exp_f32_e32 v45, v3
	v_sub_f32_e32 v3, v31, v26
	v_add_f32_e32 v2, v76, v2
	v_exp_f32_e32 v47, v3
	v_sub_f32_e32 v3, v30, v26
	v_add_f32_e32 v2, v40, v2
	v_exp_f32_e32 v48, v3
	v_sub_f32_e32 v3, v29, v26
	v_add_f32_e32 v2, v43, v2
	v_exp_f32_e32 v49, v3
	v_sub_f32_e32 v3, v28, v26
	v_add_f32_e32 v2, v45, v2
	v_exp_f32_e32 v50, v3
	v_sub_f32_e32 v3, v27, v26
	v_add_f32_e32 v2, v47, v2
	v_exp_f32_e32 v52, v3
	v_add_f32_e32 v2, v48, v2
	v_add_f32_e32 v2, v49, v2
	v_add_f32_e32 v2, v50, v2
	v_add_f32_e32 v2, v52, v2
	v_mov_b32_e32 v3, v2
	v_mov_b32_e32 v206, v2
	s_nop 1
	v_permlane32_swap_b32 v3, v206
	v_add_f32_e32 v2, v3, v206
	v_fma_f32 v3, v149, s94, -v26
	v_exp_f32_e32 v3, v3
	s_nop 0
	v_add_f32_e32 v34, v3, v2
	v_cvt_pk_bf16_f32 v2, v18, v19
	v_cvt_pk_bf16_f32 v3, v20, v21
	v_cvt_pk_bf16_f32 v4, v22, v23
	v_cvt_pk_bf16_f32 v5, v24, v25
	ds_read_b128 v[6:9], v107 offset:36864
	s_waitcnt lgkmcnt(0)
	v_mfma_f32_32x32x16_bf16 v[18:33], v[6:9], v[2:5], 0
	ds_read_b128 v[6:9], v106 offset:36864
	v_cvt_pk_bf16_f32 v158, v35, v36
	v_cvt_pk_bf16_f32 v159, v38, v39
	v_cvt_pk_bf16_f32 v160, v44, v54
	v_cvt_pk_bf16_f32 v161, v58, v60
	ds_read_b128 v[162:165], v107 offset:36896
	v_add_u32_e32 v35, v137, v131
	s_waitcnt lgkmcnt(0)
	v_mfma_f32_32x32x16_bf16 v[18:33], v[162:165], v[158:161], v[18:33]
	ds_read_b128 v[162:165], v106 offset:36896
	v_cvt_pk_bf16_f32 v36, v37, v41
	v_cvt_pk_bf16_f32 v37, v46, v51
	v_cvt_pk_bf16_f32 v38, v56, v63
	v_cvt_pk_bf16_f32 v39, v70, v75
	v_add_u32_e32 v44, v137, v132
	v_mfma_f32_32x32x16_bf16 v[2:17], v[6:9], v[2:5], 0
	s_waitcnt lgkmcnt(0)
	v_mfma_f32_32x32x16_bf16 v[2:17], v[162:165], v[158:161], v[2:17]
	ds_read_b128 v[178:181], v105 offset:36864
	ds_read_b128 v[182:185], v104 offset:36864
	ds_read_b128 v[186:189], v105 offset:36896
	s_waitcnt lgkmcnt(2)
	v_mfma_f32_32x32x16_bf16 v[18:33], v[178:181], v[36:39], v[18:33]
	ds_read_b128 v[190:193], v104 offset:36896
	s_waitcnt lgkmcnt(2)
	v_mfma_f32_32x32x16_bf16 v[2:17], v[182:185], v[36:39], v[2:17]
	v_cvt_pk_bf16_f32 v36, v42, v53
	v_cvt_pk_bf16_f32 v37, v57, v59
	v_cvt_pk_bf16_f32 v38, v66, v78
	v_cvt_pk_bf16_f32 v39, v82, v85
	ds_read_b128 v[178:181], v103 offset:36864
	s_waitcnt lgkmcnt(2)
	v_mfma_f32_32x32x16_bf16 v[18:33], v[186:189], v[36:39], v[18:33]
	ds_read_b128 v[182:185], v102 offset:36864
	s_waitcnt lgkmcnt(2)
	v_mfma_f32_32x32x16_bf16 v[2:17], v[190:193], v[36:39], v[2:17]
	v_cvt_pk_bf16_f32 v36, v55, v62
	v_cvt_pk_bf16_f32 v37, v68, v74
	v_cvt_pk_bf16_f32 v38, v80, v88
	v_cvt_pk_bf16_f32 v39, v94, v109
	ds_read_b128 v[186:189], v103 offset:36896
	s_waitcnt lgkmcnt(2)
	v_mfma_f32_32x32x16_bf16 v[18:33], v[178:181], v[36:39], v[18:33]
	ds_read_b128 v[190:193], v102 offset:36896
	s_waitcnt lgkmcnt(2)
	v_mfma_f32_32x32x16_bf16 v[2:17], v[182:185], v[36:39], v[2:17]
	v_cvt_pk_bf16_f32 v36, v64, v77
	v_cvt_pk_bf16_f32 v37, v81, v83
	v_cvt_pk_bf16_f32 v38, v90, v150
	v_cvt_pk_bf16_f32 v39, v152, v153
	ds_read_b128 v[178:181], v101 offset:36864
	s_waitcnt lgkmcnt(2)
	v_mfma_f32_32x32x16_bf16 v[18:33], v[186:189], v[36:39], v[18:33]
	ds_read_b128 v[182:185], v100 offset:36864
	s_waitcnt lgkmcnt(2)
	v_mfma_f32_32x32x16_bf16 v[2:17], v[190:193], v[36:39], v[2:17]
	v_cvt_pk_bf16_f32 v36, v79, v86
	v_cvt_pk_bf16_f32 v37, v92, v97
	v_cvt_pk_bf16_f32 v38, v151, v154
	v_cvt_pk_bf16_f32 v39, v155, v156
	ds_read_b128 v[186:189], v101 offset:36896
	s_waitcnt lgkmcnt(2)
	v_mfma_f32_32x32x16_bf16 v[18:33], v[178:181], v[36:39], v[18:33]
	ds_read_b128 v[190:193], v100 offset:36896
	s_waitcnt lgkmcnt(2)
	v_mfma_f32_32x32x16_bf16 v[2:17], v[182:185], v[36:39], v[2:17]
	v_cvt_pk_bf16_f32 v36, v84, v87
	v_cvt_pk_bf16_f32 v37, v89, v91
	v_cvt_pk_bf16_f32 v38, v93, v95
	v_cvt_pk_bf16_f32 v39, v96, v108
	ds_read_b128 v[178:181], v35 offset:36864
	s_waitcnt lgkmcnt(2)
	v_mfma_f32_32x32x16_bf16 v[18:33], v[186:189], v[36:39], v[18:33]
	ds_read_b128 v[182:185], v44 offset:36864
	s_waitcnt lgkmcnt(2)
	v_mfma_f32_32x32x16_bf16 v[2:17], v[190:193], v[36:39], v[2:17]
	v_cvt_pk_bf16_f32 v36, v61, v65
	v_cvt_pk_bf16_f32 v37, v67, v69
	v_cvt_pk_bf16_f32 v38, v71, v72
	v_cvt_pk_bf16_f32 v39, v73, v76
	ds_read_b128 v[186:189], v35 offset:36896
	s_waitcnt lgkmcnt(2)
	v_mfma_f32_32x32x16_bf16 v[18:33], v[178:181], v[36:39], v[18:33]
	ds_read_b128 v[190:193], v44 offset:36896
	s_waitcnt lgkmcnt(2)
	v_mfma_f32_32x32x16_bf16 v[2:17], v[182:185], v[36:39], v[2:17]
	v_cvt_pk_bf16_f32 v36, v40, v43
	v_cvt_pk_bf16_f32 v37, v45, v47
	v_cvt_pk_bf16_f32 v38, v48, v49
	v_cvt_pk_bf16_f32 v39, v50, v52
	v_div_scale_f32 v35, s[48:49], v34, v34, 1.0
	s_waitcnt lgkmcnt(1)
	v_mfma_f32_32x32x16_bf16 v[18:33], v[186:189], v[36:39], v[18:33]
	s_waitcnt lgkmcnt(0)
	v_mfma_f32_32x32x16_bf16 v[2:17], v[190:193], v[36:39], v[2:17]
	v_rcp_f32_e32 v36, v35
	s_nop 0
	v_fma_f32 v37, -v35, v36, 1.0
	v_fmac_f32_e32 v36, v37, v36
	v_div_scale_f32 v37, vcc, 1.0, v34, 1.0
	v_mul_f32_e32 v38, v37, v36
	v_fma_f32 v39, -v35, v38, v37
	v_fmac_f32_e32 v38, v39, v36
	v_fma_f32 v35, -v35, v38, v37
	v_div_fmas_f32 v35, v35, v36, v38
	v_div_fixup_f32 v36, v35, v34, 1.0
	v_lshlrev_b64 v[34:35], 11, v[98:99]
	v_bfe_u32 v204, v0, 5, 1
	v_lshl_add_u64 v[34:35], v[126:127], 0, v[34:35]
	v_lshlrev_b32_e32 v204, 3, v204
	v_mov_b32_e32 v205, 0
	v_mul_f32_e32 v18, v18, v36
	v_mul_f32_e32 v19, v19, v36
	v_cvt_pk_bf16_f32 v18, v18, v19
	v_mul_f32_e32 v19, v20, v36
	v_mul_f32_e32 v20, v21, v36
	v_cvt_pk_bf16_f32 v19, v19, v20
	v_mul_f32_e32 v20, v22, v36
	v_mul_f32_e32 v21, v23, v36
	v_cvt_pk_bf16_f32 v20, v20, v21
	v_mul_f32_e32 v21, v24, v36
	v_mul_f32_e32 v22, v25, v36
	v_cvt_pk_bf16_f32 v21, v21, v22
	v_lshl_add_u64 v[34:35], v[34:35], 0, v[204:205]
	v_mul_f32_e32 v26, v26, v36
	v_mul_f32_e32 v27, v27, v36
	v_cvt_pk_bf16_f32 v26, v26, v27
	v_mul_f32_e32 v27, v28, v36
	v_mul_f32_e32 v28, v29, v36
	v_cvt_pk_bf16_f32 v27, v27, v28
	v_mul_f32_e32 v28, v30, v36
	v_mul_f32_e32 v29, v31, v36
	v_cvt_pk_bf16_f32 v28, v28, v29
	v_mul_f32_e32 v29, v32, v36
	v_mul_f32_e32 v30, v33, v36
	v_cvt_pk_bf16_f32 v29, v29, v30
	v_permlane32_swap_b32 v18, v20
	v_permlane32_swap_b32 v19, v21
	global_store_dwordx4 v[34:35], v[18:21], off
	v_permlane32_swap_b32 v26, v28
	v_permlane32_swap_b32 v27, v29
	global_store_dwordx4 v[34:35], v[26:29], off offset:32
	v_mul_f32_e32 v2, v2, v36
	v_mul_f32_e32 v3, v3, v36
	v_cvt_pk_bf16_f32 v2, v2, v3
	v_mul_f32_e32 v3, v4, v36
	v_mul_f32_e32 v4, v5, v36
	v_cvt_pk_bf16_f32 v3, v3, v4
	v_mul_f32_e32 v4, v6, v36
	v_mul_f32_e32 v5, v7, v36
	v_cvt_pk_bf16_f32 v4, v4, v5
	v_mul_f32_e32 v5, v8, v36
	v_mul_f32_e32 v6, v9, v36
	v_cvt_pk_bf16_f32 v5, v5, v6
	v_mul_f32_e32 v10, v10, v36
	v_mul_f32_e32 v11, v11, v36
	v_cvt_pk_bf16_f32 v10, v10, v11
	v_mul_f32_e32 v11, v12, v36
	v_mul_f32_e32 v12, v13, v36
	v_cvt_pk_bf16_f32 v11, v11, v12
	v_mul_f32_e32 v12, v14, v36
	v_mul_f32_e32 v13, v15, v36
	v_cvt_pk_bf16_f32 v12, v12, v13
	v_mul_f32_e32 v13, v16, v36
	v_mul_f32_e32 v14, v17, v36
	v_cvt_pk_bf16_f32 v13, v13, v14
	v_permlane32_swap_b32 v2, v4
	v_permlane32_swap_b32 v3, v5
	global_store_dwordx4 v[34:35], v[2:5], off offset:64
	v_permlane32_swap_b32 v10, v12
	v_permlane32_swap_b32 v11, v13
	global_store_dwordx4 v[34:35], v[10:13], off offset:96
	s_cbranch_scc0 .LBB0_821
